# S5 chunk scan as packed complex multiply-add (two v_pk_fma_f32 per row, bit-identical to the scalar FMAs) with ds_read2st64_b32 fetches
# speedup vs baseline: 1.1345x; 1.0042x over previous
.LBB0_500:
	v_add_u32_e32 v45, 0x10000, v44
	v_add_u32_e32 v50, 0x10000, v39
	ds_read2st64_b32 v[46:47], v45 offset0:0 offset1:1
	ds_read2st64_b32 v[48:49], v45 offset0:2 offset1:3
	ds_read2st64_b32 v[52:53], v45 offset0:4 offset1:5
	ds_read2st64_b32 v[54:55], v45 offset0:6 offset1:7
	s_waitcnt lgkmcnt(0)
.Lscan_loop:
	s_waitcnt lgkmcnt(8)
	ds_read2st64_b32 v[56:57], v45 offset0:8 offset1:9
	ds_read2st64_b32 v[58:59], v45 offset0:10 offset1:11
	ds_read2st64_b32 v[60:61], v45 offset0:12 offset1:13
	ds_read2st64_b32 v[34:35], v45 offset0:14 offset1:15
	v_cvt_pk_bf16_f32 v51, v36, v37
	v_pk_fma_f32 v[160:161], v[36:37], v[32:33], v[46:47] op_sel_hi:[1,0,1]
	ds_write_b16 v50, v51
	ds_write_b16_d16_hi v50, v51 offset:128
	v_pk_fma_f32 v[158:159], v[36:37], v[32:33], v[160:161] op_sel:[1,1,0] op_sel_hi:[0,1,1] neg_lo:[0,1,0]
	v_cvt_pk_bf16_f32 v62, v158, v159
	v_pk_fma_f32 v[160:161], v[158:159], v[32:33], v[48:49] op_sel_hi:[1,0,1]
	ds_write_b16 v50, v62 offset:528
	ds_write_b16_d16_hi v50, v62 offset:656
	v_pk_fma_f32 v[36:37], v[158:159], v[32:33], v[160:161] op_sel:[1,1,0] op_sel_hi:[0,1,1] neg_lo:[0,1,0]
	v_cvt_pk_bf16_f32 v51, v36, v37
	v_pk_fma_f32 v[160:161], v[36:37], v[32:33], v[52:53] op_sel_hi:[1,0,1]
	ds_write_b16 v50, v51 offset:1056
	ds_write_b16_d16_hi v50, v51 offset:1184
	v_pk_fma_f32 v[158:159], v[36:37], v[32:33], v[160:161] op_sel:[1,1,0] op_sel_hi:[0,1,1] neg_lo:[0,1,0]
	v_cvt_pk_bf16_f32 v62, v158, v159
	v_pk_fma_f32 v[160:161], v[158:159], v[32:33], v[54:55] op_sel_hi:[1,0,1]
	ds_write_b16 v50, v62 offset:1584
	ds_write_b16_d16_hi v50, v62 offset:1712
	v_pk_fma_f32 v[36:37], v[158:159], v[32:33], v[160:161] op_sel:[1,1,0] op_sel_hi:[0,1,1] neg_lo:[0,1,0]
	s_waitcnt lgkmcnt(8)
	ds_read2st64_b32 v[46:47], v45 offset0:16 offset1:17
	ds_read2st64_b32 v[48:49], v45 offset0:18 offset1:19
	ds_read2st64_b32 v[52:53], v45 offset0:20 offset1:21
	ds_read2st64_b32 v[54:55], v45 offset0:22 offset1:23
	v_cvt_pk_bf16_f32 v51, v36, v37
	v_pk_fma_f32 v[160:161], v[36:37], v[32:33], v[56:57] op_sel_hi:[1,0,1]
	ds_write_b16 v50, v51 offset:2112
	ds_write_b16_d16_hi v50, v51 offset:2240
	v_pk_fma_f32 v[158:159], v[36:37], v[32:33], v[160:161] op_sel:[1,1,0] op_sel_hi:[0,1,1] neg_lo:[0,1,0]
	v_cvt_pk_bf16_f32 v62, v158, v159
	v_pk_fma_f32 v[160:161], v[158:159], v[32:33], v[58:59] op_sel_hi:[1,0,1]
	ds_write_b16 v50, v62 offset:2640
	ds_write_b16_d16_hi v50, v62 offset:2768
	v_pk_fma_f32 v[36:37], v[158:159], v[32:33], v[160:161] op_sel:[1,1,0] op_sel_hi:[0,1,1] neg_lo:[0,1,0]
	v_cvt_pk_bf16_f32 v51, v36, v37
	v_pk_fma_f32 v[160:161], v[36:37], v[32:33], v[60:61] op_sel_hi:[1,0,1]
	ds_write_b16 v50, v51 offset:3168
	ds_write_b16_d16_hi v50, v51 offset:3296
	v_pk_fma_f32 v[158:159], v[36:37], v[32:33], v[160:161] op_sel:[1,1,0] op_sel_hi:[0,1,1] neg_lo:[0,1,0]
	v_cvt_pk_bf16_f32 v62, v158, v159
	v_pk_fma_f32 v[160:161], v[158:159], v[32:33], v[34:35] op_sel_hi:[1,0,1]
	ds_write_b16 v50, v62 offset:3696
	ds_write_b16_d16_hi v50, v62 offset:3824
	v_pk_fma_f32 v[36:37], v[158:159], v[32:33], v[160:161] op_sel:[1,1,0] op_sel_hi:[0,1,1] neg_lo:[0,1,0]
	s_waitcnt lgkmcnt(8)
	ds_read2st64_b32 v[56:57], v45 offset0:24 offset1:25
	ds_read2st64_b32 v[58:59], v45 offset0:26 offset1:27
	ds_read2st64_b32 v[60:61], v45 offset0:28 offset1:29
	ds_read2st64_b32 v[34:35], v45 offset0:30 offset1:31
	v_cvt_pk_bf16_f32 v51, v36, v37
	v_pk_fma_f32 v[160:161], v[36:37], v[32:33], v[46:47] op_sel_hi:[1,0,1]
	ds_write_b16 v50, v51 offset:4224
	ds_write_b16_d16_hi v50, v51 offset:4352
	v_pk_fma_f32 v[158:159], v[36:37], v[32:33], v[160:161] op_sel:[1,1,0] op_sel_hi:[0,1,1] neg_lo:[0,1,0]
	v_cvt_pk_bf16_f32 v62, v158, v159
	v_pk_fma_f32 v[160:161], v[158:159], v[32:33], v[48:49] op_sel_hi:[1,0,1]
	ds_write_b16 v50, v62 offset:4752
	ds_write_b16_d16_hi v50, v62 offset:4880
	v_pk_fma_f32 v[36:37], v[158:159], v[32:33], v[160:161] op_sel:[1,1,0] op_sel_hi:[0,1,1] neg_lo:[0,1,0]
	v_cvt_pk_bf16_f32 v51, v36, v37
	v_pk_fma_f32 v[160:161], v[36:37], v[32:33], v[52:53] op_sel_hi:[1,0,1]
	ds_write_b16 v50, v51 offset:5280
	ds_write_b16_d16_hi v50, v51 offset:5408
	v_pk_fma_f32 v[158:159], v[36:37], v[32:33], v[160:161] op_sel:[1,1,0] op_sel_hi:[0,1,1] neg_lo:[0,1,0]
	v_cvt_pk_bf16_f32 v62, v158, v159
	v_pk_fma_f32 v[160:161], v[158:159], v[32:33], v[54:55] op_sel_hi:[1,0,1]
	ds_write_b16 v50, v62 offset:5808
	ds_write_b16_d16_hi v50, v62 offset:5936
	v_pk_fma_f32 v[36:37], v[158:159], v[32:33], v[160:161] op_sel:[1,1,0] op_sel_hi:[0,1,1] neg_lo:[0,1,0]
	s_waitcnt lgkmcnt(8)
	ds_read2st64_b32 v[46:47], v45 offset0:32 offset1:33
	ds_read2st64_b32 v[48:49], v45 offset0:34 offset1:35
	ds_read2st64_b32 v[52:53], v45 offset0:36 offset1:37
	ds_read2st64_b32 v[54:55], v45 offset0:38 offset1:39
	v_cvt_pk_bf16_f32 v51, v36, v37
	v_pk_fma_f32 v[160:161], v[36:37], v[32:33], v[56:57] op_sel_hi:[1,0,1]
	ds_write_b16 v50, v51 offset:6336
	ds_write_b16_d16_hi v50, v51 offset:6464
	v_pk_fma_f32 v[158:159], v[36:37], v[32:33], v[160:161] op_sel:[1,1,0] op_sel_hi:[0,1,1] neg_lo:[0,1,0]
	v_cvt_pk_bf16_f32 v62, v158, v159
	v_pk_fma_f32 v[160:161], v[158:159], v[32:33], v[58:59] op_sel_hi:[1,0,1]
	ds_write_b16 v50, v62 offset:6864
	ds_write_b16_d16_hi v50, v62 offset:6992
	v_pk_fma_f32 v[36:37], v[158:159], v[32:33], v[160:161] op_sel:[1,1,0] op_sel_hi:[0,1,1] neg_lo:[0,1,0]
	v_cvt_pk_bf16_f32 v51, v36, v37
	v_pk_fma_f32 v[160:161], v[36:37], v[32:33], v[60:61] op_sel_hi:[1,0,1]
	ds_write_b16 v50, v51 offset:7392
	ds_write_b16_d16_hi v50, v51 offset:7520
	v_pk_fma_f32 v[158:159], v[36:37], v[32:33], v[160:161] op_sel:[1,1,0] op_sel_hi:[0,1,1] neg_lo:[0,1,0]
	v_cvt_pk_bf16_f32 v62, v158, v159
	v_pk_fma_f32 v[160:161], v[158:159], v[32:33], v[34:35] op_sel_hi:[1,0,1]
	ds_write_b16 v50, v62 offset:7920
	ds_write_b16_d16_hi v50, v62 offset:8048
	v_pk_fma_f32 v[36:37], v[158:159], v[32:33], v[160:161] op_sel:[1,1,0] op_sel_hi:[0,1,1] neg_lo:[0,1,0]
	v_add_u32_e32 v45, 0x2000, v45
	v_add_u32_e32 v50, 0x2000, v50
	s_add_i32 s0, s0, 16
	s_cmpk_lt_u32 s0, 0x70
	s_cbranch_scc1 .Lscan_loop
	s_waitcnt lgkmcnt(0)
